# prep weight transposes: GEMV workgroups take three items per wave, the 1152 leftover items go to the 64 workgroups that skipped the GEMV (stride 512 past item 6143)
# speedup vs baseline: 1.0037x; 1.0037x over previous
.LBB0_363:
	v_readlane_b32 s3, v240, 51
	s_waitcnt vmcnt(0) lgkmcnt(0)
	s_barrier
	v_add_u32_e32 v1, s3, v33
	s_movk_i32 s3, 0x1c80
	v_cmp_gt_i32_e32 vcc, s3, v1
	s_and_saveexec_b64 s[4:5], vcc
	s_cbranch_execz .LBB0_386
	s_movk_i32 s3, 0x2200
	v_mul_lo_u32 v0, v33, s3
	v_add_u32_e32 v4, 0, v0
	v_lshrrev_b32_e32 v3, 5, v32
	v_and_b32_e32 v0, 31, v211
	v_lshlrev_b32_e32 v2, 2, v0
	v_mul_u32_u24_e32 v5, 0x84, v3
	v_add3_u32 v14, v4, v2, v5
	v_lshlrev_b32_e32 v2, 3, v32
	v_lshrrev_b32_e32 v15, 3, v32
	v_and_b32_e32 v2, 56, v2
	v_mul_u32_u24_e32 v5, 0x84, v2
	v_lshlrev_b32_e32 v6, 2, v15
	v_lshlrev_b32_e32 v164, 1, v2
	v_add3_u32 v16, v4, v5, v6
	s_add_u32 s6, s66, 0x2300000
	v_lshl_add_u64 v[6:7], s[66:67], 0, v[164:165]
	s_mov_b64 s[10:11], 0x5300000
	s_addc_u32 s7, s67, 0
	v_lshl_add_u64 v[4:5], v[6:7], 0, s[10:11]
	s_mov_b64 s[10:11], 0x2700000
	s_add_u32 s8, s66, 0x1b00000
	v_lshl_add_u64 v[6:7], v[6:7], 0, s[10:11]
	v_readlane_b32 s10, v240, 56
	v_or_b32_e32 v17, 8, v15
	v_or_b32_e32 v18, 16, v15
	v_or_b32_e32 v19, 24, v15
	s_addc_u32 s9, s67, 0
	v_lshlrev_b32_e32 v20, 5, v1
	s_lshl_b32 s3, s10, 5
	v_lshlrev_b32_e32 v21, 1, v1
	s_lshl_b32 s33, s10, 1
	s_mov_b64 s[10:11], 0
	s_movk_i32 s12, 0x200
	v_cmp_gt_u32_e32 vcc, s12, v1
	v_mov_b32_e32 v64, 0x17ff
	v_mov_b32_e32 v65, 0x1c7f
	s_nop 1
	v_cndmask_b32_e32 v64, v64, v65, vcc
	s_branch .LBB0_367

.LBB0_366:
	s_or_b64 exec, exec, s[12:13]
	s_movk_i32 s12, 0x17ff
	v_cmp_lt_u32_e32 vcc, s12, v1
	v_mov_b32_e32 v62, 0x800
	s_nop 0
	v_cndmask_b32_e64 v63, 0, 2, vcc
	v_lshrrev_b32_e32 v63, v63, v62
	v_add_u32_e32 v1, v63, v1
	v_lshl_add_u32 v20, v63, 5, v20
	v_lshl_add_u32 v21, v63, 1, v21
	v_cmp_lt_i32_e32 vcc, v64, v1
	s_or_b64 s[10:11], vcc, s[10:11]
	s_andn2_b64 exec, exec, s[10:11]
	s_cbranch_execz .LBB0_386
